# LB3: LB2 with the guard flag fetched by an asynchronous scalar load at the phase-15 barrier arrival (no wait on the arrival path)
# speedup vs baseline: 1.0003x; 1.0003x over previous
; __device__ __forceinline__ unsigned xb_add(unsigned* p, unsigned v) { return __hip_atomic_fetch_add(p, v, __ATOMIC_RELAXED, __HIP_MEMORY_SCOPE_AGENT); }
; __device__ __forceinline__ void xcd_barrier(const XcdBarrier& b) {
;     asm volatile("s_waitcnt vmcnt(0)" ::: "memory");
;     __syncthreads();
;     if (threadIdx.x == 0) {
;         unsigned* bar = b.bar;
;         __builtin_amdgcn_s_waitcnt(0);
;         unsigned nloc = b.st[0], nx = b.st[1];
;         if (nloc == 0u) { xcd_barrier_complete(bar, b.x, nloc, nx); b.st[0] = nloc; b.st[1] = nx; }
;         const unsigned old = xb_add(&bar[XB_XSUB(b.x)], 1u);
; __global__ void __launch_bounds__(NWAVES * 64, 2) fwd_kernel(Args args) {
;     ...
;         const bool last_ = (ph == args.ph_hi - 1) && ((ph2 & 1) || !((PHASE_REP >> ph) & 1));
;         if (!MK_PER_PHASE && !last_ && ph != 12) xcd_barrier(bar);
;         else __syncthreads();
.Lxg_n0:
	v_readlane_b32 s4, v243, 16
	s_cmp_lg_u32 s4, 15
	s_cbranch_scc1 .Lxg_n15
	s_add_u32 s4, s80, 0xf000
	s_addc_u32 s5, s81, 0
	s_load_dword s32, s[4:5], 0x0 glc

; __global__ void __launch_bounds__(NWAVES * 64, 2) fwd_kernel(Args args) {
;     ...
;         const bool last_ = (ph == args.ph_hi - 1) && ((ph2 & 1) || !((PHASE_REP >> ph) & 1));
;         if (!MK_PER_PHASE && !last_ && ph != 12) xcd_barrier(bar);
;         else __syncthreads();
.LBB0_1263:
	v_readlane_b32 s4, v243, 16
	s_sub_i32 s4, s4, 16
	s_cmp_lt_u32 s4, 3
	s_cbranch_scc0 .Lbar_full
	s_waitcnt lgkmcnt(0)
	s_cmp_eq_u32 s32, 0
	s_cbranch_scc1 .Lbar_local
